# B-attention loop: K/V LDS-DMA issue deferred into late PV MFMA gaps (after MFMAs 14,15); scalar slot arithmetic left in place
# speedup vs baseline: 1.0094x; 1.0011x over previous
.LBB0_489:
	s_mov_b32 s14, s47
	v_mov_b64_e32 v[176:177], v[64:65]
	s_mov_b32 s21, s19
	v_lshl_add_u32 v168, s18, 13, v187
	ds_read_b64_tr_b16 v[164:165], v168 offset:24576
	ds_read_b64_tr_b16 v[166:167], v168 offset:25088
	v_add_f32_e32 v64, v48, v49
	v_add_f32_e32 v64, v50, v64
	v_add_f32_e32 v64, v51, v64
	v_add_f32_e32 v64, v52, v64
	v_add_f32_e32 v64, v53, v64
	v_cvt_pk_bf16_f32 v108, v48, v49
	v_cvt_pk_bf16_f32 v109, v50, v51
	s_waitcnt lgkmcnt(9)
	v_mfma_f32_32x32x16_bf16 v[80:95], v[156:159], v[120:123], 0
	ds_read_b64_tr_b16 v[156:157], v168 offset:28672
	ds_read_b64_tr_b16 v[158:159], v168 offset:29184
	v_add_f32_e32 v48, v54, v64
	s_waitcnt lgkmcnt(10)
	v_mfma_f32_32x32x16_bf16 v[64:79], v[148:151], v[120:123], 0
	v_add_f32_e32 v48, v55, v48
	v_add_f32_e32 v48, v56, v48
	v_add_f32_e32 v96, v57, v48
	v_cvt_pk_bf16_f32 v110, v52, v53
	v_cvt_pk_bf16_f32 v111, v54, v55
	ds_read_b64_tr_b16 v[48:49], v168 offset:25600
	ds_read_b64_tr_b16 v[50:51], v168 offset:26112
	v_add_f32_e32 v52, v58, v96
	v_add_f32_e32 v52, v59, v52
	v_add_f32_e32 v52, v60, v52
	v_add_f32_e32 v96, v61, v52
	v_cvt_pk_bf16_f32 v104, v56, v57
	v_cvt_pk_bf16_f32 v105, v58, v59
	s_waitcnt lgkmcnt(11)
	v_mfma_f32_32x32x16_bf16 v[80:95], v[152:155], v[124:127], v[80:95]
	ds_read_b64_tr_b16 v[52:53], v168 offset:29696
	ds_read_b64_tr_b16 v[54:55], v168 offset:30208
	s_waitcnt lgkmcnt(12)
	v_mfma_f32_32x32x16_bf16 v[64:79], v[144:147], v[124:127], v[64:79]
	v_add_f32_e32 v56, v62, v96
	v_add_f32_e32 v56, v63, v56
	v_add_f32_e32 v56, v32, v56
	v_add_f32_e32 v96, v33, v56
	v_cvt_pk_bf16_f32 v106, v60, v61
	v_cvt_pk_bf16_f32 v107, v62, v63
	ds_read_b64_tr_b16 v[56:57], v168 offset:26624
	ds_read_b64_tr_b16 v[58:59], v168 offset:27136
	v_add_f32_e32 v60, v34, v96
	v_add_f32_e32 v60, v35, v60
	v_add_f32_e32 v60, v36, v60
	v_add_f32_e32 v60, v37, v60
	v_cvt_pk_bf16_f32 v100, v32, v33
	v_cvt_pk_bf16_f32 v101, v34, v35
	s_waitcnt lgkmcnt(13)
	v_mfma_f32_32x32x16_bf16 v[80:95], v[140:143], v[116:119], v[80:95]
	ds_read_b64_tr_b16 v[32:33], v168 offset:30720
	ds_read_b64_tr_b16 v[34:35], v168 offset:31232
	s_waitcnt lgkmcnt(14)
	v_mfma_f32_32x32x16_bf16 v[64:79], v[136:139], v[116:119], v[64:79]
	v_add_f32_e32 v60, v38, v60
	v_add_f32_e32 v60, v39, v60
	v_add_f32_e32 v60, v40, v60
	v_add_f32_e32 v60, v41, v60
	v_cvt_pk_bf16_f32 v102, v36, v37
	v_cvt_pk_bf16_f32 v103, v38, v39
	ds_read_b64_tr_b16 v[36:37], v168 offset:27648
	ds_read_b64_tr_b16 v[38:39], v168 offset:28160
	v_add_f32_e32 v60, v42, v60
	v_add_f32_e32 v60, v43, v60
	v_add_f32_e32 v60, v44, v60
	v_add_f32_e32 v60, v45, v60
	v_cvt_pk_bf16_f32 v96, v40, v41
	v_cvt_pk_bf16_f32 v97, v42, v43
	s_waitcnt lgkmcnt(14)
	v_mfma_f32_32x32x16_bf16 v[80:95], v[132:135], v[112:115], v[80:95]
	ds_read_b64_tr_b16 v[40:41], v168 offset:31744
	ds_read_b64_tr_b16 v[42:43], v168 offset:32256
	v_mfma_f32_32x32x16_bf16 v[64:79], v[128:131], v[112:115], v[64:79]
	v_add_f32_e32 v60, v46, v60
	v_add_f32_e32 v60, v47, v60
	v_add_f32_e32 v60, 0, v60
	v_cvt_pk_bf16_f32 v98, v44, v45
	v_cvt_pk_bf16_f32 v99, v46, v47
	v_lshl_add_u64 v[246:247], v[162:163], 0, s[0:1]
	s_lshl_b32 s3, s46, 13
	s_add_i32 s98, s3, s36
	v_lshl_add_u64 v[248:249], v[160:161], 0, s[0:1]
	s_lshl_b32 s33, s47, 13
	s_add_i32 s99, s33, s37
	v_add_f32_e32 v168, v188, v60
	s_waitcnt lgkmcnt(14)
	v_mfma_f32_32x32x16_bf16 v[0:15], v[108:111], v[164:167], v[0:15]
	v_exp_f32_e32 v80, v80
	v_exp_f32_e32 v81, v81
	v_exp_f32_e32 v82, v82
	v_exp_f32_e32 v83, v83
	s_waitcnt lgkmcnt(12)
	v_mfma_f32_32x32x16_bf16 v[16:31], v[108:111], v[156:159], v[16:31]
	v_exp_f32_e32 v84, v84
	v_exp_f32_e32 v85, v85
	v_exp_f32_e32 v86, v86
	v_exp_f32_e32 v87, v87
	v_add_u32_e32 v60, s33, v185
	ds_read_b128 v[44:47], v60
	ds_read_b128 v[136:139], v60 offset:512
	s_waitcnt lgkmcnt(12)
	v_mfma_f32_32x32x16_bf16 v[0:15], v[104:107], v[48:51], v[0:15]
	v_exp_f32_e32 v88, v88
	v_exp_f32_e32 v89, v89
	v_exp_f32_e32 v90, v90
	v_exp_f32_e32 v91, v91
	ds_read_b128 v[140:143], v60 offset:2048
	ds_read_b128 v[144:147], v60 offset:2560
	s_waitcnt lgkmcnt(12)
	v_mfma_f32_32x32x16_bf16 v[16:31], v[104:107], v[52:55], v[16:31]
	v_exp_f32_e32 v92, v92
	v_exp_f32_e32 v93, v93
	v_exp_f32_e32 v94, v94
	v_exp_f32_e32 v95, v95
	ds_read_b128 v[148:151], v60 offset:4096
	ds_read_b128 v[152:155], v60 offset:4608
	s_waitcnt lgkmcnt(12)
	v_mfma_f32_32x32x16_bf16 v[0:15], v[100:103], v[56:59], v[0:15]
	v_exp_f32_e32 v64, v64
	v_exp_f32_e32 v65, v65
	v_exp_f32_e32 v66, v66
	v_exp_f32_e32 v67, v67
	ds_read_b128 v[156:159], v60 offset:6144
	ds_read_b128 v[128:131], v60 offset:6656
	s_waitcnt lgkmcnt(12)
	v_mfma_f32_32x32x16_bf16 v[16:31], v[100:103], v[32:35], v[16:31]
	v_exp_f32_e32 v68, v68
	v_exp_f32_e32 v69, v69
	v_exp_f32_e32 v70, v70
	v_exp_f32_e32 v71, v71
	s_mov_b64 s[16:17], 0xb622100
	v_lshl_add_u64 v[250:251], v[246:247], 0, s[16:17]
	s_mov_b32 m0, s98
	s_nop 0
	global_load_lds_dwordx4 v[250:251], off
	s_waitcnt lgkmcnt(10)
	v_mfma_f32_32x32x16_bf16 v[0:15], v[96:99], v[36:39], v[0:15]
	v_exp_f32_e32 v72, v72
	v_exp_f32_e32 v73, v73
	v_exp_f32_e32 v74, v74
	v_exp_f32_e32 v75, v75
	s_mov_b64 s[16:17], 0xb412200
	v_lshl_add_u64 v[250:251], v[248:249], 0, s[16:17]
	s_mov_b32 m0, s99
	s_nop 0
	global_load_lds_dwordx4 v[250:251], off
	s_waitcnt lgkmcnt(8)
	v_mfma_f32_32x32x16_bf16 v[16:31], v[96:99], v[40:43], v[16:31]
	v_exp_f32_e32 v76, v76
	v_exp_f32_e32 v77, v77
	v_exp_f32_e32 v78, v78
	v_exp_f32_e32 v79, v79
	s_waitcnt vmcnt(2) lgkmcnt(0)
	s_barrier
	s_add_i32 s15, s47, 1
	s_cmp_lg_u32 s47, 2
	s_cselect_b32 s46, s15, 0
	v_add_u32_e32 v169, s3, v187
	ds_read_b64_tr_b16 v[164:165], v169 offset:24576
	ds_read_b64_tr_b16 v[166:167], v169 offset:25088
	s_waitcnt lgkmcnt(9)
	v_mfma_f32_32x32x16_bf16 v[48:63], v[44:47], v[120:123], 0
	v_add_f32_e32 v32, v80, v81
	v_add_f32_e32 v32, v82, v32
	v_add_f32_e32 v32, v83, v32
	v_add_f32_e32 v32, v84, v32
	v_add_f32_e32 v32, v85, v32
	v_cvt_pk_bf16_f32 v108, v80, v81
	v_cvt_pk_bf16_f32 v109, v82, v83
	ds_read_b64_tr_b16 v[80:81], v169 offset:28672
	ds_read_b64_tr_b16 v[82:83], v169 offset:29184
	v_add_f32_e32 v32, v86, v32
	v_add_f32_e32 v32, v87, v32
	v_add_f32_e32 v32, v88, v32
	v_add_f32_e32 v96, v89, v32
	s_waitcnt lgkmcnt(10)
	v_mfma_f32_32x32x16_bf16 v[32:47], v[136:139], v[120:123], 0
	v_cvt_pk_bf16_f32 v110, v84, v85
	v_cvt_pk_bf16_f32 v111, v86, v87
	ds_read_b64_tr_b16 v[84:85], v169 offset:25600
	ds_read_b64_tr_b16 v[86:87], v169 offset:26112
	s_waitcnt lgkmcnt(11)
	v_mfma_f32_32x32x16_bf16 v[48:63], v[140:143], v[124:127], v[48:63]
	v_add_f32_e32 v96, v90, v96
	v_add_f32_e32 v96, v91, v96
	v_add_f32_e32 v96, v92, v96
	v_add_f32_e32 v96, v93, v96
	v_cvt_pk_bf16_f32 v104, v88, v89
	v_cvt_pk_bf16_f32 v105, v90, v91
	ds_read_b64_tr_b16 v[88:89], v169 offset:29696
	ds_read_b64_tr_b16 v[90:91], v169 offset:30208
	s_waitcnt lgkmcnt(12)
	v_mfma_f32_32x32x16_bf16 v[32:47], v[144:147], v[124:127], v[32:47]
	v_add_f32_e32 v96, v94, v96
	v_add_f32_e32 v96, v95, v96
	v_add_f32_e32 v96, v64, v96
	v_add_f32_e32 v96, v65, v96
	v_cvt_pk_bf16_f32 v106, v92, v93
	v_cvt_pk_bf16_f32 v107, v94, v95
	ds_read_b64_tr_b16 v[92:93], v169 offset:26624
	ds_read_b64_tr_b16 v[94:95], v169 offset:27136
	s_waitcnt lgkmcnt(13)
	v_mfma_f32_32x32x16_bf16 v[48:63], v[148:151], v[116:119], v[48:63]
	v_add_f32_e32 v96, v66, v96
	v_add_f32_e32 v96, v67, v96
	v_add_f32_e32 v96, v68, v96
	v_add_f32_e32 v96, v69, v96
	v_cvt_pk_bf16_f32 v100, v64, v65
	v_cvt_pk_bf16_f32 v101, v66, v67
	ds_read_b64_tr_b16 v[64:65], v169 offset:30720
	ds_read_b64_tr_b16 v[66:67], v169 offset:31232
	s_waitcnt lgkmcnt(14)
	v_mfma_f32_32x32x16_bf16 v[32:47], v[152:155], v[116:119], v[32:47]
	v_add_f32_e32 v96, v70, v96
	v_add_f32_e32 v96, v71, v96
	v_add_f32_e32 v96, v72, v96
	v_add_f32_e32 v96, v73, v96
	v_cvt_pk_bf16_f32 v102, v68, v69
	v_cvt_pk_bf16_f32 v103, v70, v71
	ds_read_b64_tr_b16 v[68:69], v169 offset:27648
	ds_read_b64_tr_b16 v[70:71], v169 offset:28160
	s_waitcnt lgkmcnt(14)
	v_mfma_f32_32x32x16_bf16 v[48:63], v[156:159], v[112:115], v[48:63]
	v_add_f32_e32 v96, v74, v96
	v_add_f32_e32 v96, v75, v96
	v_add_f32_e32 v96, v76, v96
	v_add_f32_e32 v136, v77, v96
	v_cvt_pk_bf16_f32 v96, v72, v73
	v_cvt_pk_bf16_f32 v97, v74, v75
	ds_read_b64_tr_b16 v[72:73], v169 offset:31744
	ds_read_b64_tr_b16 v[74:75], v169 offset:32256
	v_mfma_f32_32x32x16_bf16 v[32:47], v[128:131], v[112:115], v[32:47]
	v_add_f32_e32 v98, v78, v136
	v_add_f32_e32 v98, v79, v98
	v_add_f32_e32 v128, 0, v98
	v_cvt_pk_bf16_f32 v98, v76, v77
	v_cvt_pk_bf16_f32 v99, v78, v79
	s_add_i32 s98, s33, s36
	s_lshl_b32 s15, s46, 13
	s_add_i32 s99, s15, s37
	v_add_f32_e32 v188, v168, v128
	s_add_i32 s20, s20, 2
	s_waitcnt lgkmcnt(14)
	v_mfma_f32_32x32x16_bf16 v[0:15], v[108:111], v[164:167], v[0:15]
	v_exp_f32_e32 v48, v48
	v_exp_f32_e32 v49, v49
	v_exp_f32_e32 v50, v50
	v_exp_f32_e32 v51, v51
	s_waitcnt lgkmcnt(12)
	v_mfma_f32_32x32x16_bf16 v[16:31], v[108:111], v[80:83], v[16:31]
	v_exp_f32_e32 v52, v52
	v_exp_f32_e32 v53, v53
	v_exp_f32_e32 v54, v54
	v_exp_f32_e32 v55, v55
	v_add_u32_e32 v76, s15, v185
	ds_read_b128 v[156:159], v76
	ds_read_b128 v[148:151], v76 offset:512
	s_waitcnt lgkmcnt(12)
	v_mfma_f32_32x32x16_bf16 v[0:15], v[104:107], v[84:87], v[0:15]
	v_exp_f32_e32 v56, v56
	v_exp_f32_e32 v57, v57
	v_exp_f32_e32 v58, v58
	v_exp_f32_e32 v59, v59
	ds_read_b128 v[152:155], v76 offset:2048
	ds_read_b128 v[144:147], v76 offset:2560
	s_waitcnt lgkmcnt(12)
	v_mfma_f32_32x32x16_bf16 v[16:31], v[104:107], v[88:91], v[16:31]
	v_exp_f32_e32 v60, v60
	v_exp_f32_e32 v61, v61
	v_exp_f32_e32 v62, v62
	v_exp_f32_e32 v63, v63
	ds_read_b128 v[140:143], v76 offset:4096
	ds_read_b128 v[136:139], v76 offset:4608
	s_waitcnt lgkmcnt(12)
	v_mfma_f32_32x32x16_bf16 v[0:15], v[100:103], v[92:95], v[0:15]
	v_exp_f32_e32 v32, v32
	v_exp_f32_e32 v33, v33
	v_exp_f32_e32 v34, v34
	v_exp_f32_e32 v35, v35
	ds_read_b128 v[132:135], v76 offset:6144
	ds_read_b128 v[128:131], v76 offset:6656
	s_waitcnt lgkmcnt(12)
	v_mfma_f32_32x32x16_bf16 v[16:31], v[100:103], v[64:67], v[16:31]
	v_exp_f32_e32 v36, v36
	v_exp_f32_e32 v37, v37
	v_exp_f32_e32 v38, v38
	v_exp_f32_e32 v39, v39
	s_mov_b64 s[16:17], 0xb72a100
	v_lshl_add_u64 v[250:251], v[246:247], 0, s[16:17]
	s_mov_b32 m0, s98
	s_nop 0
	global_load_lds_dwordx4 v[250:251], off
	s_waitcnt lgkmcnt(10)
	v_mfma_f32_32x32x16_bf16 v[0:15], v[96:99], v[68:71], v[0:15]
	v_exp_f32_e32 v40, v40
	v_exp_f32_e32 v41, v41
	v_exp_f32_e32 v42, v42
	v_exp_f32_e32 v43, v43
	s_mov_b64 s[16:17], 0xb51a200
	v_lshl_add_u64 v[250:251], v[248:249], 0, s[16:17]
	s_mov_b32 m0, s99
	s_nop 0
	global_load_lds_dwordx4 v[250:251], off
	s_waitcnt lgkmcnt(8)
	v_mfma_f32_32x32x16_bf16 v[16:31], v[96:99], v[72:75], v[16:31]
	v_exp_f32_e32 v44, v44
	v_exp_f32_e32 v45, v45
	v_exp_f32_e32 v46, v46
	v_exp_f32_e32 v47, v47
	s_add_i32 s3, s46, 1
	s_waitcnt vmcnt(2) lgkmcnt(0)
	s_barrier
	s_cmp_lg_u32 s46, 2
	s_cselect_b32 s47, s3, 0
	s_add_i32 s19, s19, 2
	v_lshl_add_u64 v[160:161], v[160:161], 0, s[12:13]
	v_lshl_add_u64 v[162:163], v[162:163], 0, s[12:13]
	s_cmp_ge_u32 s20, s42
	v_lshl_add_u64 v[64:65], v[176:177], 0, s[12:13]
	s_mov_b32 s18, s14
	s_cbranch_scc0 .LBB0_489
	s_add_i32 s0, s20, 1
	s_cmp_ge_u32 s0, s41
	s_cbranch_scc1 .LBB0_524

	.amdhsa_kernel _Z14fwd_megakernel6Params
		.amdhsa_group_segment_fixed_size 0
		.amdhsa_private_segment_fixed_size 0
		.amdhsa_kernarg_size 760
		.amdhsa_user_sgpr_count 2
		.amdhsa_user_sgpr_dispatch_ptr 0
		.amdhsa_user_sgpr_queue_ptr 0
		.amdhsa_user_sgpr_kernarg_segment_ptr 1
		.amdhsa_user_sgpr_dispatch_id 0
		.amdhsa_user_sgpr_kernarg_preload_length 0
		.amdhsa_user_sgpr_kernarg_preload_offset 0
		.amdhsa_user_sgpr_private_segment_size 0
		.amdhsa_uses_dynamic_stack 0
		.amdhsa_enable_private_segment 0
		.amdhsa_system_sgpr_workgroup_id_x 1
		.amdhsa_system_sgpr_workgroup_id_y 0
		.amdhsa_system_sgpr_workgroup_id_z 0
		.amdhsa_system_sgpr_workgroup_info 0
		.amdhsa_system_vgpr_workitem_id 2
		.amdhsa_next_free_vgpr 255
		.amdhsa_next_free_sgpr 102
		.amdhsa_accum_offset 256
		.amdhsa_reserve_vcc 1
		.amdhsa_float_round_mode_32 0
		.amdhsa_float_round_mode_16_64 0
		.amdhsa_float_denorm_mode_32 3
		.amdhsa_float_denorm_mode_16_64 3
		.amdhsa_dx10_clamp 1
		.amdhsa_ieee_mode 1
		.amdhsa_fp16_overflow 0
		.amdhsa_tg_split 0
		.amdhsa_exception_fp_ieee_invalid_op 0
		.amdhsa_exception_fp_denorm_src 0
		.amdhsa_exception_fp_ieee_div_zero 0
		.amdhsa_exception_fp_ieee_overflow 0
		.amdhsa_exception_fp_ieee_underflow 0
		.amdhsa_exception_fp_ieee_inexact 0
		.amdhsa_exception_int_div_zero 0
	.end_amdhsa_kernel

amdhsa.kernels:
  - .agpr_count:     0
    .args:
      - .offset:         0
        .size:           504
        .value_kind:     by_value
      - .offset:         504
        .size:           4
        .value_kind:     hidden_block_count_x
      - .offset:         508
        .size:           4
        .value_kind:     hidden_block_count_y
      - .offset:         512
        .size:           4
        .value_kind:     hidden_block_count_z
      - .offset:         516
        .size:           2
        .value_kind:     hidden_group_size_x
      - .offset:         518
        .size:           2
        .value_kind:     hidden_group_size_y
      - .offset:         520
        .size:           2
        .value_kind:     hidden_group_size_z
      - .offset:         522
        .size:           2
        .value_kind:     hidden_remainder_x
      - .offset:         524
        .size:           2
        .value_kind:     hidden_remainder_y
      - .offset:         526
        .size:           2
        .value_kind:     hidden_remainder_z
      - .offset:         544
        .size:           8
        .value_kind:     hidden_global_offset_x
      - .offset:         552
        .size:           8
        .value_kind:     hidden_global_offset_y
      - .offset:         560
        .size:           8
        .value_kind:     hidden_global_offset_z
      - .offset:         568
        .size:           2
        .value_kind:     hidden_grid_dims
      - .offset:         592
        .size:           8
        .value_kind:     hidden_multigrid_sync_arg
      - .offset:         624
        .size:           4
        .value_kind:     hidden_dynamic_lds_size
    .group_segment_fixed_size: 0
    .kernarg_segment_align: 8
    .kernarg_segment_size: 760
    .language:       OpenCL C
    .language_version:
      - 2
      - 0
    .max_flat_workgroup_size: 512
    .name:           _Z14fwd_megakernel6Params
    .private_segment_fixed_size: 0
    .sgpr_count:     108
    .sgpr_spill_count: 144
    .symbol:         _Z14fwd_megakernel6Params.kd
    .uniform_work_group_size: 1
    .uses_dynamic_stack: false
    .vgpr_count:     255
    .vgpr_spill_count: 0
    .wavefront_size: 64
